# r6_nt plus nt on the final-layer f32 output stores of the residual epilogue (never re-read)
# baseline (speedup 1.0000x reference)
; __device__ __forceinline__ const unsigned char* xrow(const XBuf& b, int row) { return (row < b.split ? b.p0 : b.p1) + (size_t)row * (b.f32 ? 8192 : 4096); }
; __device__ __forceinline__ void xstore8(const XBuf& b, int row, int col, const float* v) {
;     unsigned char* r = (unsigned char*)xrow(b, row);
;     if (b.f32) { *(f32x4*)(r + (size_t)col * 4) = (f32x4){v[0], v[1], v[2], v[3]}; *(f32x4*)(r + (size_t)col * 4 + 16) = (f32x4){v[4], v[5], v[6], v[7]}; }
;     __device__ __forceinline__ void operator()(const f32x4 (&acc)[2][2][4][2], const Unit& u, int wr, int wc, int fr, int fq) const {
;     ...
;             for (int m = 0; m < 4; ++m) { const int row = row0 + ai * HALF + m * 16;
;                 float xv[2][8];
; #pragma unroll
;                 for (int bj = 0; bj < 2; ++bj) xload8(xin, row, col0 + bj * HALF, xv[bj]);
; #pragma unroll
;                 for (int bj = 0; bj < 2; ++bj) { float o[8];
; #pragma unroll
;                     for (int j = 0; j < 4; ++j) { o[j] = xv[bj][j] + gv[bj][0][j] * acc[ai][bj][m][0][j]; o[4 + j] = xv[bj][4 + j] + gv[bj][1][j] * acc[ai][bj][m][1][j]; }
;                     xstore8(xout, row, col0 + bj * HALF, o); }
.Lepi_res_j0:
	v_pk_fma_f32 v[124:125], v[124:125], v[140:141], v[144:145]
	v_mov_b32_e32 v144, s53
	v_mov_b32_e32 v145, s51
	v_cmp_gt_i32_e32 vcc, s54, v202
	v_pk_fma_f32 v[126:127], v[126:127], v[142:143], v[146:147]
	v_mov_b32_e32 v146, s52
	v_cndmask_b32_e32 v145, v144, v145, vcc
	v_mov_b32_e32 v144, s33
	v_cndmask_b32_e32 v144, v144, v146, vcc
	v_lshlrev_b64 v[146:147], s67, v[202:203]
	v_lshl_add_u64 v[144:145], v[144:145], 0, v[146:147]
	v_cndmask_b32_e64 v146, 0, 1, s[8:9]
	v_pk_fma_f32 v[120:121], v[120:121], v[136:137], v[148:149]
	v_pk_fma_f32 v[122:123], v[122:123], v[138:139], v[150:151]
	v_cmp_ne_u32_e64 s[4:5], 1, v146
	s_andn2_b64 vcc, exec, s[8:9]
	s_mov_b64 s[2:3], -1
	s_cbranch_vccnz .LBB0_564
	v_lshl_add_u64 v[146:147], v[198:199], 2, v[144:145]
	s_mov_b64 s[2:3], 0
	global_store_dwordx4 v[146:147], v[124:127], off nt
	global_store_dwordx4 v[146:147], v[120:123], off offset:16 nt

; __device__ __forceinline__ const unsigned char* xrow(const XBuf& b, int row) { return (row < b.split ? b.p0 : b.p1) + (size_t)row * (b.f32 ? 8192 : 4096); }
; __device__ __forceinline__ void xstore8(const XBuf& b, int row, int col, const float* v) {
;     unsigned char* r = (unsigned char*)xrow(b, row);
;     if (b.f32) { *(f32x4*)(r + (size_t)col * 4) = (f32x4){v[0], v[1], v[2], v[3]}; *(f32x4*)(r + (size_t)col * 4 + 16) = (f32x4){v[4], v[5], v[6], v[7]}; }
;     __device__ __forceinline__ void operator()(const f32x4 (&acc)[2][2][4][2], const Unit& u, int wr, int wc, int fr, int fq) const {
;     ...
;                 for (int bj = 0; bj < 2; ++bj) { float o[8];
; #pragma unroll
;                     for (int j = 0; j < 4; ++j) { o[j] = xv[bj][j] + gv[bj][0][j] * acc[ai][bj][m][0][j]; o[4 + j] = xv[bj][4 + j] + gv[bj][1][j] * acc[ai][bj][m][1][j]; }
;                     xstore8(xout, row, col0 + bj * HALF, o); }
.LBB0_566:
	v_pk_fma_f32 v[116:117], v[116:117], v[132:133], v[152:153]
	v_pk_fma_f32 v[112:113], v[112:113], v[128:129], v[156:157]
	v_pk_fma_f32 v[118:119], v[118:119], v[134:135], v[154:155]
	v_pk_fma_f32 v[114:115], v[114:115], v[130:131], v[158:159]
	s_and_b64 vcc, exec, s[4:5]
	s_mov_b64 s[2:3], -1
	s_cbranch_vccnz .LBB0_568
	v_lshl_add_u64 v[120:121], v[200:201], 2, v[144:145]
	s_mov_b64 s[2:3], 0
	global_store_dwordx4 v[120:121], v[116:119], off nt
	global_store_dwordx4 v[120:121], v[112:115], off offset:16 nt

; __device__ __forceinline__ const unsigned char* xrow(const XBuf& b, int row) { return (row < b.split ? b.p0 : b.p1) + (size_t)row * (b.f32 ? 8192 : 4096); }
; __device__ __forceinline__ void xstore8(const XBuf& b, int row, int col, const float* v) {
;     unsigned char* r = (unsigned char*)xrow(b, row);
;     if (b.f32) { *(f32x4*)(r + (size_t)col * 4) = (f32x4){v[0], v[1], v[2], v[3]}; *(f32x4*)(r + (size_t)col * 4 + 16) = (f32x4){v[4], v[5], v[6], v[7]}; }
;     __device__ __forceinline__ void operator()(const f32x4 (&acc)[2][2][4][2], const Unit& u, int wr, int wc, int fr, int fq) const {
;     ...
;             for (int m = 0; m < 4; ++m) { const int row = row0 + ai * HALF + m * 16;
;                 float xv[2][8];
; #pragma unroll
;                 for (int bj = 0; bj < 2; ++bj) xload8(xin, row, col0 + bj * HALF, xv[bj]);
; #pragma unroll
;                 for (int bj = 0; bj < 2; ++bj) { float o[8];
; #pragma unroll
;                     for (int j = 0; j < 4; ++j) { o[j] = xv[bj][j] + gv[bj][0][j] * acc[ai][bj][m][0][j]; o[4 + j] = xv[bj][4 + j] + gv[bj][1][j] * acc[ai][bj][m][1][j]; }
;                     xstore8(xout, row, col0 + bj * HALF, o); }
.Lepi_res_j1:
	v_pk_fma_f32 v[108:109], v[108:109], v[140:141], v[112:113]
	v_mov_b32_e32 v112, s53
	v_mov_b32_e32 v113, s51
	v_cmp_gt_i32_e32 vcc, s54, v144
	v_pk_fma_f32 v[110:111], v[110:111], v[142:143], v[114:115]
	v_mov_b32_e32 v114, s52
	v_cndmask_b32_e32 v113, v112, v113, vcc
	v_mov_b32_e32 v112, s33
	v_cndmask_b32_e32 v112, v112, v114, vcc
	v_lshlrev_b64 v[114:115], s67, v[144:145]
	v_pk_fma_f32 v[104:105], v[104:105], v[136:137], v[116:117]
	v_pk_fma_f32 v[106:107], v[106:107], v[138:139], v[118:119]
	v_lshl_add_u64 v[112:113], v[112:113], 0, v[114:115]
	s_and_b64 vcc, exec, s[4:5]
	s_mov_b64 s[2:3], -1
	s_cbranch_vccnz .LBB0_580
	v_lshl_add_u64 v[114:115], v[198:199], 2, v[112:113]
	s_mov_b64 s[2:3], 0
	global_store_dwordx4 v[114:115], v[108:111], off nt
	global_store_dwordx4 v[114:115], v[104:107], off offset:16 nt

; __device__ __forceinline__ const unsigned char* xrow(const XBuf& b, int row) { return (row < b.split ? b.p0 : b.p1) + (size_t)row * (b.f32 ? 8192 : 4096); }
; __device__ __forceinline__ void xstore8(const XBuf& b, int row, int col, const float* v) {
;     unsigned char* r = (unsigned char*)xrow(b, row);
;     if (b.f32) { *(f32x4*)(r + (size_t)col * 4) = (f32x4){v[0], v[1], v[2], v[3]}; *(f32x4*)(r + (size_t)col * 4 + 16) = (f32x4){v[4], v[5], v[6], v[7]}; }
;     __device__ __forceinline__ void operator()(const f32x4 (&acc)[2][2][4][2], const Unit& u, int wr, int wc, int fr, int fq) const {
;     ...
;                 for (int bj = 0; bj < 2; ++bj) { float o[8];
; #pragma unroll
;                     for (int j = 0; j < 4; ++j) { o[j] = xv[bj][j] + gv[bj][0][j] * acc[ai][bj][m][0][j]; o[4 + j] = xv[bj][4 + j] + gv[bj][1][j] * acc[ai][bj][m][1][j]; }
;                     xstore8(xout, row, col0 + bj * HALF, o); }
.LBB0_582:
	v_pk_fma_f32 v[100:101], v[100:101], v[132:133], v[120:121]
	v_pk_fma_f32 v[96:97], v[96:97], v[128:129], v[124:125]
	v_pk_fma_f32 v[102:103], v[102:103], v[134:135], v[122:123]
	v_pk_fma_f32 v[98:99], v[98:99], v[130:131], v[126:127]
	s_and_b64 vcc, exec, s[4:5]
	s_mov_b64 s[2:3], -1
	s_cbranch_vccnz .LBB0_584
	v_lshl_add_u64 v[104:105], v[200:201], 2, v[112:113]
	s_mov_b64 s[2:3], 0
	global_store_dwordx4 v[104:105], v[100:103], off nt
	global_store_dwordx4 v[104:105], v[96:99], off offset:16 nt

; __device__ __forceinline__ const unsigned char* xrow(const XBuf& b, int row) { return (row < b.split ? b.p0 : b.p1) + (size_t)row * (b.f32 ? 8192 : 4096); }
; __device__ __forceinline__ void xstore8(const XBuf& b, int row, int col, const float* v) {
;     unsigned char* r = (unsigned char*)xrow(b, row);
;     if (b.f32) { *(f32x4*)(r + (size_t)col * 4) = (f32x4){v[0], v[1], v[2], v[3]}; *(f32x4*)(r + (size_t)col * 4 + 16) = (f32x4){v[4], v[5], v[6], v[7]}; }
;     __device__ __forceinline__ void operator()(const f32x4 (&acc)[2][2][4][2], const Unit& u, int wr, int wc, int fr, int fq) const {
;     ...
;             for (int m = 0; m < 4; ++m) { const int row = row0 + ai * HALF + m * 16;
;                 float xv[2][8];
; #pragma unroll
;                 for (int bj = 0; bj < 2; ++bj) xload8(xin, row, col0 + bj * HALF, xv[bj]);
; #pragma unroll
;                 for (int bj = 0; bj < 2; ++bj) { float o[8];
; #pragma unroll
;                     for (int j = 0; j < 4; ++j) { o[j] = xv[bj][j] + gv[bj][0][j] * acc[ai][bj][m][0][j]; o[4 + j] = xv[bj][4 + j] + gv[bj][1][j] * acc[ai][bj][m][1][j]; }
;                     xstore8(xout, row, col0 + bj * HALF, o); }
.Lepi_res_j2:
	v_pk_fma_f32 v[92:93], v[92:93], v[140:141], v[96:97]
	v_mov_b32_e32 v96, s53
	v_mov_b32_e32 v97, s51
	v_cmp_gt_i32_e32 vcc, s54, v112
	v_pk_fma_f32 v[94:95], v[94:95], v[142:143], v[98:99]
	v_mov_b32_e32 v98, s52
	v_cndmask_b32_e32 v97, v96, v97, vcc
	v_mov_b32_e32 v96, s33
	v_cndmask_b32_e32 v96, v96, v98, vcc
	v_lshlrev_b64 v[98:99], s67, v[112:113]
	v_pk_fma_f32 v[88:89], v[88:89], v[136:137], v[100:101]
	v_pk_fma_f32 v[90:91], v[90:91], v[138:139], v[102:103]
	v_lshl_add_u64 v[96:97], v[96:97], 0, v[98:99]
	s_and_b64 vcc, exec, s[4:5]
	s_mov_b64 s[2:3], -1
	s_cbranch_vccnz .LBB0_596
	v_lshl_add_u64 v[98:99], v[198:199], 2, v[96:97]
	s_mov_b64 s[2:3], 0
	global_store_dwordx4 v[98:99], v[92:95], off nt
	global_store_dwordx4 v[98:99], v[88:91], off offset:16 nt

; __device__ __forceinline__ const unsigned char* xrow(const XBuf& b, int row) { return (row < b.split ? b.p0 : b.p1) + (size_t)row * (b.f32 ? 8192 : 4096); }
; __device__ __forceinline__ void xstore8(const XBuf& b, int row, int col, const float* v) {
;     unsigned char* r = (unsigned char*)xrow(b, row);
;     if (b.f32) { *(f32x4*)(r + (size_t)col * 4) = (f32x4){v[0], v[1], v[2], v[3]}; *(f32x4*)(r + (size_t)col * 4 + 16) = (f32x4){v[4], v[5], v[6], v[7]}; }
;     __device__ __forceinline__ void operator()(const f32x4 (&acc)[2][2][4][2], const Unit& u, int wr, int wc, int fr, int fq) const {
;     ...
;                 for (int bj = 0; bj < 2; ++bj) { float o[8];
; #pragma unroll
;                     for (int j = 0; j < 4; ++j) { o[j] = xv[bj][j] + gv[bj][0][j] * acc[ai][bj][m][0][j]; o[4 + j] = xv[bj][4 + j] + gv[bj][1][j] * acc[ai][bj][m][1][j]; }
;                     xstore8(xout, row, col0 + bj * HALF, o); }
.LBB0_598:
	v_pk_fma_f32 v[84:85], v[84:85], v[132:133], v[104:105]
	v_pk_fma_f32 v[80:81], v[80:81], v[128:129], v[108:109]
	v_pk_fma_f32 v[86:87], v[86:87], v[134:135], v[106:107]
	v_pk_fma_f32 v[82:83], v[82:83], v[130:131], v[110:111]
	s_and_b64 vcc, exec, s[4:5]
	s_mov_b64 s[2:3], -1
	s_cbranch_vccnz .LBB0_600
	v_lshl_add_u64 v[88:89], v[200:201], 2, v[96:97]
	s_mov_b64 s[2:3], 0
	global_store_dwordx4 v[88:89], v[84:87], off nt
	global_store_dwordx4 v[88:89], v[80:83], off offset:16 nt

; __device__ __forceinline__ const unsigned char* xrow(const XBuf& b, int row) { return (row < b.split ? b.p0 : b.p1) + (size_t)row * (b.f32 ? 8192 : 4096); }
; __device__ __forceinline__ void xstore8(const XBuf& b, int row, int col, const float* v) {
;     unsigned char* r = (unsigned char*)xrow(b, row);
;     if (b.f32) { *(f32x4*)(r + (size_t)col * 4) = (f32x4){v[0], v[1], v[2], v[3]}; *(f32x4*)(r + (size_t)col * 4 + 16) = (f32x4){v[4], v[5], v[6], v[7]}; }
;     __device__ __forceinline__ void operator()(const f32x4 (&acc)[2][2][4][2], const Unit& u, int wr, int wc, int fr, int fq) const {
;     ...
;             for (int m = 0; m < 4; ++m) { const int row = row0 + ai * HALF + m * 16;
;                 float xv[2][8];
; #pragma unroll
;                 for (int bj = 0; bj < 2; ++bj) xload8(xin, row, col0 + bj * HALF, xv[bj]);
; #pragma unroll
;                 for (int bj = 0; bj < 2; ++bj) { float o[8];
; #pragma unroll
;                     for (int j = 0; j < 4; ++j) { o[j] = xv[bj][j] + gv[bj][0][j] * acc[ai][bj][m][0][j]; o[4 + j] = xv[bj][4 + j] + gv[bj][1][j] * acc[ai][bj][m][1][j]; }
;                     xstore8(xout, row, col0 + bj * HALF, o); }
.Lepi_res_j3:
	v_pk_fma_f32 v[76:77], v[76:77], v[140:141], v[80:81]
	v_mov_b32_e32 v80, s53
	v_mov_b32_e32 v81, s51
	v_cmp_gt_i32_e32 vcc, s54, v96
	v_pk_fma_f32 v[78:79], v[78:79], v[142:143], v[82:83]
	v_mov_b32_e32 v82, s52
	v_cndmask_b32_e32 v81, v80, v81, vcc
	v_mov_b32_e32 v80, s33
	v_cndmask_b32_e32 v80, v80, v82, vcc
	v_lshlrev_b64 v[82:83], s67, v[96:97]
	v_pk_fma_f32 v[72:73], v[72:73], v[136:137], v[84:85]
	v_pk_fma_f32 v[74:75], v[74:75], v[138:139], v[86:87]
	v_lshl_add_u64 v[80:81], v[80:81], 0, v[82:83]
	s_and_b64 vcc, exec, s[4:5]
	s_mov_b64 s[2:3], -1
	s_cbranch_vccnz .LBB0_612
	v_lshl_add_u64 v[82:83], v[198:199], 2, v[80:81]
	s_mov_b64 s[2:3], 0
	global_store_dwordx4 v[82:83], v[76:79], off nt
	global_store_dwordx4 v[82:83], v[72:75], off offset:16 nt

; __device__ __forceinline__ const unsigned char* xrow(const XBuf& b, int row) { return (row < b.split ? b.p0 : b.p1) + (size_t)row * (b.f32 ? 8192 : 4096); }
; __device__ __forceinline__ void xstore8(const XBuf& b, int row, int col, const float* v) {
;     unsigned char* r = (unsigned char*)xrow(b, row);
;     if (b.f32) { *(f32x4*)(r + (size_t)col * 4) = (f32x4){v[0], v[1], v[2], v[3]}; *(f32x4*)(r + (size_t)col * 4 + 16) = (f32x4){v[4], v[5], v[6], v[7]}; }
;     __device__ __forceinline__ void operator()(const f32x4 (&acc)[2][2][4][2], const Unit& u, int wr, int wc, int fr, int fq) const {
;     ...
;                 for (int bj = 0; bj < 2; ++bj) { float o[8];
; #pragma unroll
;                     for (int j = 0; j < 4; ++j) { o[j] = xv[bj][j] + gv[bj][0][j] * acc[ai][bj][m][0][j]; o[4 + j] = xv[bj][4 + j] + gv[bj][1][j] * acc[ai][bj][m][1][j]; }
;                     xstore8(xout, row, col0 + bj * HALF, o); }
.LBB0_614:
	v_pk_fma_f32 v[68:69], v[68:69], v[132:133], v[88:89]
	v_pk_fma_f32 v[64:65], v[64:65], v[128:129], v[92:93]
	v_pk_fma_f32 v[70:71], v[70:71], v[134:135], v[90:91]
	v_pk_fma_f32 v[66:67], v[66:67], v[130:131], v[94:95]
	s_and_b64 vcc, exec, s[4:5]
	s_mov_b64 s[2:3], -1
	s_cbranch_vccnz .LBB0_616
	v_lshl_add_u64 v[72:73], v[200:201], 2, v[80:81]
	s_mov_b64 s[2:3], 0
	global_store_dwordx4 v[72:73], v[68:71], off nt
	global_store_dwordx4 v[72:73], v[64:67], off offset:16 nt

; __device__ __forceinline__ const unsigned char* xrow(const XBuf& b, int row) { return (row < b.split ? b.p0 : b.p1) + (size_t)row * (b.f32 ? 8192 : 4096); }
; __device__ __forceinline__ void xstore8(const XBuf& b, int row, int col, const float* v) {
;     unsigned char* r = (unsigned char*)xrow(b, row);
;     if (b.f32) { *(f32x4*)(r + (size_t)col * 4) = (f32x4){v[0], v[1], v[2], v[3]}; *(f32x4*)(r + (size_t)col * 4 + 16) = (f32x4){v[4], v[5], v[6], v[7]}; }
;     __device__ __forceinline__ void operator()(const f32x4 (&acc)[2][2][4][2], const Unit& u, int wr, int wc, int fr, int fq) const {
;     ...
;             for (int m = 0; m < 4; ++m) { const int row = row0 + ai * HALF + m * 16;
;                 float xv[2][8];
; #pragma unroll
;                 for (int bj = 0; bj < 2; ++bj) xload8(xin, row, col0 + bj * HALF, xv[bj]);
; #pragma unroll
;                 for (int bj = 0; bj < 2; ++bj) { float o[8];
; #pragma unroll
;                     for (int j = 0; j < 4; ++j) { o[j] = xv[bj][j] + gv[bj][0][j] * acc[ai][bj][m][0][j]; o[4 + j] = xv[bj][4 + j] + gv[bj][1][j] * acc[ai][bj][m][1][j]; }
;                     xstore8(xout, row, col0 + bj * HALF, o); }
.Lepi_res_j4:
	v_pk_fma_f32 v[60:61], v[60:61], v[76:77], v[80:81]
	v_mov_b32_e32 v80, s53
	v_mov_b32_e32 v81, s51
	v_cmp_gt_i32_e32 vcc, s54, v96
	v_pk_fma_f32 v[62:63], v[62:63], v[78:79], v[82:83]
	v_mov_b32_e32 v82, s52
	v_cndmask_b32_e32 v81, v80, v81, vcc
	v_mov_b32_e32 v80, s33
	v_cndmask_b32_e32 v80, v80, v82, vcc
	v_lshlrev_b64 v[82:83], s67, v[96:97]
	v_pk_fma_f32 v[56:57], v[56:57], v[72:73], v[84:85]
	v_pk_fma_f32 v[58:59], v[58:59], v[74:75], v[86:87]
	v_lshl_add_u64 v[80:81], v[80:81], 0, v[82:83]
	s_and_b64 vcc, exec, s[4:5]
	s_mov_b64 s[2:3], -1
	s_cbranch_vccnz .LBB0_628
	v_lshl_add_u64 v[82:83], v[198:199], 2, v[80:81]
	s_mov_b64 s[2:3], 0
	global_store_dwordx4 v[82:83], v[60:63], off nt
	global_store_dwordx4 v[82:83], v[56:59], off offset:16 nt

; __device__ __forceinline__ const unsigned char* xrow(const XBuf& b, int row) { return (row < b.split ? b.p0 : b.p1) + (size_t)row * (b.f32 ? 8192 : 4096); }
; __device__ __forceinline__ void xstore8(const XBuf& b, int row, int col, const float* v) {
;     unsigned char* r = (unsigned char*)xrow(b, row);
;     if (b.f32) { *(f32x4*)(r + (size_t)col * 4) = (f32x4){v[0], v[1], v[2], v[3]}; *(f32x4*)(r + (size_t)col * 4 + 16) = (f32x4){v[4], v[5], v[6], v[7]}; }
;     __device__ __forceinline__ void operator()(const f32x4 (&acc)[2][2][4][2], const Unit& u, int wr, int wc, int fr, int fq) const {
;     ...
;                 for (int bj = 0; bj < 2; ++bj) { float o[8];
; #pragma unroll
;                     for (int j = 0; j < 4; ++j) { o[j] = xv[bj][j] + gv[bj][0][j] * acc[ai][bj][m][0][j]; o[4 + j] = xv[bj][4 + j] + gv[bj][1][j] * acc[ai][bj][m][1][j]; }
;                     xstore8(xout, row, col0 + bj * HALF, o); }
.LBB0_630:
	v_pk_fma_f32 v[52:53], v[52:53], v[68:69], v[88:89]
	v_pk_fma_f32 v[48:49], v[48:49], v[64:65], v[92:93]
	v_pk_fma_f32 v[54:55], v[54:55], v[70:71], v[90:91]
	v_pk_fma_f32 v[50:51], v[50:51], v[66:67], v[94:95]
	s_and_b64 vcc, exec, s[4:5]
	s_mov_b64 s[2:3], -1
	s_cbranch_vccnz .LBB0_632
	v_lshl_add_u64 v[56:57], v[200:201], 2, v[80:81]
	s_mov_b64 s[2:3], 0
	global_store_dwordx4 v[56:57], v[52:55], off nt
	global_store_dwordx4 v[56:57], v[48:51], off offset:16 nt

; __device__ __forceinline__ const unsigned char* xrow(const XBuf& b, int row) { return (row < b.split ? b.p0 : b.p1) + (size_t)row * (b.f32 ? 8192 : 4096); }
; __device__ __forceinline__ void xstore8(const XBuf& b, int row, int col, const float* v) {
;     unsigned char* r = (unsigned char*)xrow(b, row);
;     if (b.f32) { *(f32x4*)(r + (size_t)col * 4) = (f32x4){v[0], v[1], v[2], v[3]}; *(f32x4*)(r + (size_t)col * 4 + 16) = (f32x4){v[4], v[5], v[6], v[7]}; }
;     __device__ __forceinline__ void operator()(const f32x4 (&acc)[2][2][4][2], const Unit& u, int wr, int wc, int fr, int fq) const {
;     ...
;             for (int m = 0; m < 4; ++m) { const int row = row0 + ai * HALF + m * 16;
;                 float xv[2][8];
; #pragma unroll
;                 for (int bj = 0; bj < 2; ++bj) xload8(xin, row, col0 + bj * HALF, xv[bj]);
; #pragma unroll
;                 for (int bj = 0; bj < 2; ++bj) { float o[8];
; #pragma unroll
;                     for (int j = 0; j < 4; ++j) { o[j] = xv[bj][j] + gv[bj][0][j] * acc[ai][bj][m][0][j]; o[4 + j] = xv[bj][4 + j] + gv[bj][1][j] * acc[ai][bj][m][1][j]; }
;                     xstore8(xout, row, col0 + bj * HALF, o); }
.Lepi_res_j5:
	v_pk_fma_f32 v[44:45], v[44:45], v[76:77], v[48:49]
	v_mov_b32_e32 v48, s53
	v_mov_b32_e32 v49, s51
	v_cmp_gt_i32_e32 vcc, s54, v80
	v_pk_fma_f32 v[46:47], v[46:47], v[78:79], v[50:51]
	v_mov_b32_e32 v50, s52
	v_cndmask_b32_e32 v49, v48, v49, vcc
	v_mov_b32_e32 v48, s33
	v_cndmask_b32_e32 v48, v48, v50, vcc
	v_lshlrev_b64 v[50:51], s67, v[80:81]
	v_pk_fma_f32 v[40:41], v[40:41], v[72:73], v[52:53]
	v_pk_fma_f32 v[42:43], v[42:43], v[74:75], v[54:55]
	v_lshl_add_u64 v[48:49], v[48:49], 0, v[50:51]
	s_and_b64 vcc, exec, s[4:5]
	s_mov_b64 s[2:3], -1
	s_cbranch_vccnz .LBB0_644
	v_lshl_add_u64 v[50:51], v[198:199], 2, v[48:49]
	s_mov_b64 s[2:3], 0
	global_store_dwordx4 v[50:51], v[44:47], off nt
	global_store_dwordx4 v[50:51], v[40:43], off offset:16 nt

; __device__ __forceinline__ const unsigned char* xrow(const XBuf& b, int row) { return (row < b.split ? b.p0 : b.p1) + (size_t)row * (b.f32 ? 8192 : 4096); }
; __device__ __forceinline__ void xstore8(const XBuf& b, int row, int col, const float* v) {
;     unsigned char* r = (unsigned char*)xrow(b, row);
;     if (b.f32) { *(f32x4*)(r + (size_t)col * 4) = (f32x4){v[0], v[1], v[2], v[3]}; *(f32x4*)(r + (size_t)col * 4 + 16) = (f32x4){v[4], v[5], v[6], v[7]}; }
;     __device__ __forceinline__ void operator()(const f32x4 (&acc)[2][2][4][2], const Unit& u, int wr, int wc, int fr, int fq) const {
;     ...
;                 for (int bj = 0; bj < 2; ++bj) { float o[8];
; #pragma unroll
;                     for (int j = 0; j < 4; ++j) { o[j] = xv[bj][j] + gv[bj][0][j] * acc[ai][bj][m][0][j]; o[4 + j] = xv[bj][4 + j] + gv[bj][1][j] * acc[ai][bj][m][1][j]; }
;                     xstore8(xout, row, col0 + bj * HALF, o); }
.LBB0_646:
	v_pk_fma_f32 v[36:37], v[36:37], v[68:69], v[56:57]
	v_pk_fma_f32 v[32:33], v[32:33], v[64:65], v[60:61]
	v_pk_fma_f32 v[38:39], v[38:39], v[70:71], v[58:59]
	v_pk_fma_f32 v[34:35], v[34:35], v[66:67], v[62:63]
	s_and_b64 vcc, exec, s[4:5]
	s_mov_b64 s[2:3], -1
	s_cbranch_vccnz .LBB0_648
	v_lshl_add_u64 v[40:41], v[200:201], 2, v[48:49]
	s_mov_b64 s[2:3], 0
	global_store_dwordx4 v[40:41], v[36:39], off nt
	global_store_dwordx4 v[40:41], v[32:35], off offset:16 nt

; __device__ __forceinline__ const unsigned char* xrow(const XBuf& b, int row) { return (row < b.split ? b.p0 : b.p1) + (size_t)row * (b.f32 ? 8192 : 4096); }
; __device__ __forceinline__ void xstore8(const XBuf& b, int row, int col, const float* v) {
;     unsigned char* r = (unsigned char*)xrow(b, row);
;     if (b.f32) { *(f32x4*)(r + (size_t)col * 4) = (f32x4){v[0], v[1], v[2], v[3]}; *(f32x4*)(r + (size_t)col * 4 + 16) = (f32x4){v[4], v[5], v[6], v[7]}; }
;     __device__ __forceinline__ void operator()(const f32x4 (&acc)[2][2][4][2], const Unit& u, int wr, int wc, int fr, int fq) const {
;     ...
;             for (int m = 0; m < 4; ++m) { const int row = row0 + ai * HALF + m * 16;
;                 float xv[2][8];
; #pragma unroll
;                 for (int bj = 0; bj < 2; ++bj) xload8(xin, row, col0 + bj * HALF, xv[bj]);
; #pragma unroll
;                 for (int bj = 0; bj < 2; ++bj) { float o[8];
; #pragma unroll
;                     for (int j = 0; j < 4; ++j) { o[j] = xv[bj][j] + gv[bj][0][j] * acc[ai][bj][m][0][j]; o[4 + j] = xv[bj][4 + j] + gv[bj][1][j] * acc[ai][bj][m][1][j]; }
;                     xstore8(xout, row, col0 + bj * HALF, o); }
.Lepi_res_j6:
	v_pk_fma_f32 v[28:29], v[28:29], v[76:77], v[32:33]
	v_mov_b32_e32 v32, s53
	v_mov_b32_e32 v33, s51
	v_cmp_gt_i32_e32 vcc, s54, v48
	v_pk_fma_f32 v[30:31], v[30:31], v[78:79], v[34:35]
	v_mov_b32_e32 v34, s52
	v_cndmask_b32_e32 v33, v32, v33, vcc
	v_mov_b32_e32 v32, s33
	v_cndmask_b32_e32 v32, v32, v34, vcc
	v_lshlrev_b64 v[34:35], s67, v[48:49]
	v_pk_fma_f32 v[24:25], v[24:25], v[72:73], v[36:37]
	v_pk_fma_f32 v[26:27], v[26:27], v[74:75], v[38:39]
	v_lshl_add_u64 v[32:33], v[32:33], 0, v[34:35]
	s_and_b64 vcc, exec, s[4:5]
	s_mov_b64 s[2:3], -1
	s_cbranch_vccnz .LBB0_660
	v_lshl_add_u64 v[34:35], v[198:199], 2, v[32:33]
	s_mov_b64 s[2:3], 0
	global_store_dwordx4 v[34:35], v[28:31], off nt
	global_store_dwordx4 v[34:35], v[24:27], off offset:16 nt

; __device__ __forceinline__ const unsigned char* xrow(const XBuf& b, int row) { return (row < b.split ? b.p0 : b.p1) + (size_t)row * (b.f32 ? 8192 : 4096); }
; __device__ __forceinline__ void xstore8(const XBuf& b, int row, int col, const float* v) {
;     unsigned char* r = (unsigned char*)xrow(b, row);
;     if (b.f32) { *(f32x4*)(r + (size_t)col * 4) = (f32x4){v[0], v[1], v[2], v[3]}; *(f32x4*)(r + (size_t)col * 4 + 16) = (f32x4){v[4], v[5], v[6], v[7]}; }
;     __device__ __forceinline__ void operator()(const f32x4 (&acc)[2][2][4][2], const Unit& u, int wr, int wc, int fr, int fq) const {
;     ...
;                 for (int bj = 0; bj < 2; ++bj) { float o[8];
; #pragma unroll
;                     for (int j = 0; j < 4; ++j) { o[j] = xv[bj][j] + gv[bj][0][j] * acc[ai][bj][m][0][j]; o[4 + j] = xv[bj][4 + j] + gv[bj][1][j] * acc[ai][bj][m][1][j]; }
;                     xstore8(xout, row, col0 + bj * HALF, o); }
.LBB0_662:
	v_pk_fma_f32 v[20:21], v[20:21], v[68:69], v[40:41]
	v_pk_fma_f32 v[16:17], v[16:17], v[64:65], v[44:45]
	v_pk_fma_f32 v[22:23], v[22:23], v[70:71], v[42:43]
	v_pk_fma_f32 v[18:19], v[18:19], v[66:67], v[46:47]
	s_and_b64 vcc, exec, s[4:5]
	s_mov_b64 s[2:3], -1
	s_cbranch_vccnz .LBB0_664
	v_lshl_add_u64 v[24:25], v[200:201], 2, v[32:33]
	s_mov_b64 s[2:3], 0
	global_store_dwordx4 v[24:25], v[20:23], off nt
	global_store_dwordx4 v[24:25], v[16:19], off offset:16 nt

; __device__ __forceinline__ const unsigned char* xrow(const XBuf& b, int row) { return (row < b.split ? b.p0 : b.p1) + (size_t)row * (b.f32 ? 8192 : 4096); }
; __device__ __forceinline__ void xstore8(const XBuf& b, int row, int col, const float* v) {
;     unsigned char* r = (unsigned char*)xrow(b, row);
;     if (b.f32) { *(f32x4*)(r + (size_t)col * 4) = (f32x4){v[0], v[1], v[2], v[3]}; *(f32x4*)(r + (size_t)col * 4 + 16) = (f32x4){v[4], v[5], v[6], v[7]}; }
;     __device__ __forceinline__ void operator()(const f32x4 (&acc)[2][2][4][2], const Unit& u, int wr, int wc, int fr, int fq) const {
;     ...
;             for (int m = 0; m < 4; ++m) { const int row = row0 + ai * HALF + m * 16;
;                 float xv[2][8];
; #pragma unroll
;                 for (int bj = 0; bj < 2; ++bj) xload8(xin, row, col0 + bj * HALF, xv[bj]);
; #pragma unroll
;                 for (int bj = 0; bj < 2; ++bj) { float o[8];
; #pragma unroll
;                     for (int j = 0; j < 4; ++j) { o[j] = xv[bj][j] + gv[bj][0][j] * acc[ai][bj][m][0][j]; o[4 + j] = xv[bj][4 + j] + gv[bj][1][j] * acc[ai][bj][m][1][j]; }
;                     xstore8(xout, row, col0 + bj * HALF, o); }
.Lepi_res_j7:
	v_pk_fma_f32 v[12:13], v[12:13], v[76:77], v[16:17]
	v_mov_b32_e32 v16, s53
	v_mov_b32_e32 v17, s51
	v_cmp_gt_i32_e32 vcc, s54, v32
	v_pk_fma_f32 v[14:15], v[14:15], v[78:79], v[18:19]
	v_mov_b32_e32 v18, s52
	v_cndmask_b32_e32 v17, v16, v17, vcc
	v_mov_b32_e32 v16, s33
	v_cndmask_b32_e32 v16, v16, v18, vcc
	v_lshlrev_b64 v[18:19], s67, v[32:33]
	v_pk_fma_f32 v[8:9], v[8:9], v[72:73], v[20:21]
	v_pk_fma_f32 v[10:11], v[10:11], v[74:75], v[22:23]
	v_lshl_add_u64 v[16:17], v[16:17], 0, v[18:19]
	s_and_b64 vcc, exec, s[4:5]
	s_mov_b64 s[2:3], -1
	s_cbranch_vccnz .LBB0_676
	v_lshl_add_u64 v[18:19], v[198:199], 2, v[16:17]
	s_mov_b64 s[2:3], 0
	global_store_dwordx4 v[18:19], v[12:15], off nt
	global_store_dwordx4 v[18:19], v[8:11], off offset:16 nt

; __device__ __forceinline__ const unsigned char* xrow(const XBuf& b, int row) { return (row < b.split ? b.p0 : b.p1) + (size_t)row * (b.f32 ? 8192 : 4096); }
; __device__ __forceinline__ void xstore8(const XBuf& b, int row, int col, const float* v) {
;     unsigned char* r = (unsigned char*)xrow(b, row);
;     if (b.f32) { *(f32x4*)(r + (size_t)col * 4) = (f32x4){v[0], v[1], v[2], v[3]}; *(f32x4*)(r + (size_t)col * 4 + 16) = (f32x4){v[4], v[5], v[6], v[7]}; }
;     __device__ __forceinline__ void operator()(const f32x4 (&acc)[2][2][4][2], const Unit& u, int wr, int wc, int fr, int fq) const {
;     ...
;                 for (int bj = 0; bj < 2; ++bj) { float o[8];
; #pragma unroll
;                     for (int j = 0; j < 4; ++j) { o[j] = xv[bj][j] + gv[bj][0][j] * acc[ai][bj][m][0][j]; o[4 + j] = xv[bj][4 + j] + gv[bj][1][j] * acc[ai][bj][m][1][j]; }
;                     xstore8(xout, row, col0 + bj * HALF, o); }
.LBB0_678:
	v_pk_fma_f32 v[4:5], v[4:5], v[68:69], v[24:25]
	v_pk_fma_f32 v[0:1], v[0:1], v[64:65], v[28:29]
	v_pk_fma_f32 v[6:7], v[6:7], v[70:71], v[26:27]
	v_pk_fma_f32 v[2:3], v[2:3], v[66:67], v[30:31]
	s_and_b64 vcc, exec, s[4:5]
	s_mov_b64 s[2:3], -1
	s_cbranch_vccnz .LBB0_680
	v_lshl_add_u64 v[8:9], v[200:201], 2, v[16:17]
	s_mov_b64 s[2:3], 0
	global_store_dwordx4 v[8:9], v[4:7], off nt
	global_store_dwordx4 v[8:9], v[0:3], off offset:16 nt
